# GU epilogue: removed unreachable row-panel-mismatch slow paths and their flag/branch plumbing (8 diamonds, straight-line fast path)
# speedup vs baseline: 1.0081x; 1.0075x over previous
.Lzp_exit3:
	s_lshl_b32 s19, s28, 8
	v_add_u32_e32 v138, s19, v141
	ds_read_b32 v140, v143
	ds_read_b32 v215, v143 offset:64
	ds_read_b32 v216, v143 offset:128
	ds_read_b32 v217, v143 offset:192
	ds_read_b32 v218, v143 offset:512
	ds_read_b32 v219, v143 offset:576
	ds_read_b32 v220, v143 offset:640
	ds_read_b32 v221, v143 offset:704
	s_waitcnt lgkmcnt(0)
	v_mul_f32_e32 v246, 0xbfb8aa3b, v140
	v_mul_f32_e32 v247, v140, v140
	v_rcp_f32_e32 v247, v247
	v_mul_f32_e32 v120, v120, v124
	v_mul_f32_e32 v121, v121, v125
	v_mul_f32_e32 v122, v122, v126
	v_mul_f32_e32 v123, v123, v127
	v_mul_f32_e32 v112, v112, v116
	v_mul_f32_e32 v113, v113, v117
	v_mul_f32_e32 v114, v114, v118
	v_mul_f32_e32 v115, v115, v119
	v_mul_f32_e32 v124, v246, v124
	v_mul_f32_e32 v125, v246, v125
	v_mul_f32_e32 v126, v246, v126
	v_mul_f32_e32 v127, v246, v127
	v_mul_f32_e32 v116, v246, v116
	v_mul_f32_e32 v117, v246, v117
	v_mul_f32_e32 v118, v246, v118
	v_mul_f32_e32 v119, v246, v119
	v_exp_f32_e32 v124, v124
	v_exp_f32_e32 v125, v125
	v_exp_f32_e32 v126, v126
	v_exp_f32_e32 v127, v127
	v_exp_f32_e32 v116, v116
	v_exp_f32_e32 v117, v117
	v_exp_f32_e32 v118, v118
	v_exp_f32_e32 v119, v119
	v_fma_f32 v124, v124, v247, v247
	v_fma_f32 v125, v125, v247, v247
	v_fma_f32 v126, v126, v247, v247
	v_fma_f32 v127, v127, v247, v247
	v_fma_f32 v116, v116, v247, v247
	v_fma_f32 v117, v117, v247, v247
	v_fma_f32 v118, v118, v247, v247
	v_fma_f32 v119, v119, v247, v247
	v_rcp_f32_e32 v124, v124
	v_rcp_f32_e32 v125, v125
	v_rcp_f32_e32 v126, v126
	v_rcp_f32_e32 v127, v127
	v_rcp_f32_e32 v116, v116
	v_rcp_f32_e32 v117, v117
	v_rcp_f32_e32 v118, v118
	v_rcp_f32_e32 v119, v119
	v_mul_f32_e32 v120, v120, v124
	v_mul_f32_e32 v121, v121, v125
	v_mul_f32_e32 v122, v122, v126
	v_mul_f32_e32 v123, v123, v127
	v_mul_f32_e32 v112, v112, v116
	v_mul_f32_e32 v113, v113, v117
	v_mul_f32_e32 v114, v114, v118
	v_mul_f32_e32 v115, v115, v119
	v_cvt_pk_bf16_f32 v124, v120, v121
	v_cvt_pk_bf16_f32 v125, v122, v123
	v_cvt_pk_bf16_f32 v126, v112, v113
	v_cvt_pk_bf16_f32 v127, v114, v115
	s_movk_i32 s1, 0xb00
	v_lshl_or_b32 v139, s8, 7, v144
	v_mul_lo_u32 v113, v138, s1
	v_add_lshl_u32 v112, v113, v139, 1
	buffer_store_dwordx4 v[124:127], v112, s[36:39], 0 offen sc1
	v_mov_b32_e32 v112, v215
	s_waitcnt lgkmcnt(0)
	v_mul_f32_e32 v246, 0xbfb8aa3b, v112
	v_mul_f32_e32 v247, v112, v112
	v_rcp_f32_e32 v247, v247
	v_mul_f32_e32 v104, v104, v108
	v_mul_f32_e32 v105, v105, v109
	v_mul_f32_e32 v106, v106, v110
	v_mul_f32_e32 v107, v107, v111
	v_mul_f32_e32 v96, v96, v100
	v_mul_f32_e32 v97, v97, v101
	v_mul_f32_e32 v98, v98, v102
	v_mul_f32_e32 v99, v99, v103
	v_mul_f32_e32 v108, v246, v108
	v_mul_f32_e32 v109, v246, v109
	v_mul_f32_e32 v110, v246, v110
	v_mul_f32_e32 v111, v246, v111
	v_mul_f32_e32 v100, v246, v100
	v_mul_f32_e32 v101, v246, v101
	v_mul_f32_e32 v102, v246, v102
	v_mul_f32_e32 v103, v246, v103
	v_exp_f32_e32 v108, v108
	v_exp_f32_e32 v109, v109
	v_exp_f32_e32 v110, v110
	v_exp_f32_e32 v111, v111
	v_exp_f32_e32 v100, v100
	v_exp_f32_e32 v101, v101
	v_exp_f32_e32 v102, v102
	v_exp_f32_e32 v103, v103
	v_fma_f32 v108, v108, v247, v247
	v_fma_f32 v109, v109, v247, v247
	v_fma_f32 v110, v110, v247, v247
	v_fma_f32 v111, v111, v247, v247
	v_fma_f32 v100, v100, v247, v247
	v_fma_f32 v101, v101, v247, v247
	v_fma_f32 v102, v102, v247, v247
	v_fma_f32 v103, v103, v247, v247
	v_rcp_f32_e32 v108, v108
	v_rcp_f32_e32 v109, v109
	v_rcp_f32_e32 v110, v110
	v_rcp_f32_e32 v111, v111
	v_rcp_f32_e32 v100, v100
	v_rcp_f32_e32 v101, v101
	v_rcp_f32_e32 v102, v102
	v_rcp_f32_e32 v103, v103
	v_mul_f32_e32 v104, v104, v108
	v_mul_f32_e32 v105, v105, v109
	v_mul_f32_e32 v106, v106, v110
	v_mul_f32_e32 v107, v107, v111
	v_mul_f32_e32 v96, v96, v100
	v_mul_f32_e32 v97, v97, v101
	v_mul_f32_e32 v98, v98, v102
	v_mul_f32_e32 v99, v99, v103
	v_cvt_pk_bf16_f32 v108, v104, v105
	v_cvt_pk_bf16_f32 v109, v106, v107
	v_cvt_pk_bf16_f32 v110, v96, v97
	v_cvt_pk_bf16_f32 v111, v98, v99
	v_add_u32_e32 v97, 0xb000, v113
	v_add_lshl_u32 v96, v97, v139, 1
	buffer_store_dwordx4 v[108:111], v96, s[36:39], 0 offen sc1
	s_nop 1
	v_mov_b32_e32 v96, v216
	s_waitcnt lgkmcnt(0)
	v_mul_f32_e32 v246, 0xbfb8aa3b, v96
	v_mul_f32_e32 v247, v96, v96
	v_rcp_f32_e32 v247, v247
	v_mul_f32_e32 v88, v88, v92
	v_mul_f32_e32 v89, v89, v93
	v_mul_f32_e32 v90, v90, v94
	v_mul_f32_e32 v91, v91, v95
	v_mul_f32_e32 v80, v80, v84
	v_mul_f32_e32 v81, v81, v85
	v_mul_f32_e32 v82, v82, v86
	v_mul_f32_e32 v83, v83, v87
	v_mul_f32_e32 v92, v246, v92
	v_mul_f32_e32 v93, v246, v93
	v_mul_f32_e32 v94, v246, v94
	v_mul_f32_e32 v95, v246, v95
	v_mul_f32_e32 v84, v246, v84
	v_mul_f32_e32 v85, v246, v85
	v_mul_f32_e32 v86, v246, v86
	v_mul_f32_e32 v87, v246, v87
	v_exp_f32_e32 v92, v92
	v_exp_f32_e32 v93, v93
	v_exp_f32_e32 v94, v94
	v_exp_f32_e32 v95, v95
	v_exp_f32_e32 v84, v84
	v_exp_f32_e32 v85, v85
	v_exp_f32_e32 v86, v86
	v_exp_f32_e32 v87, v87
	v_fma_f32 v92, v92, v247, v247
	v_fma_f32 v93, v93, v247, v247
	v_fma_f32 v94, v94, v247, v247
	v_fma_f32 v95, v95, v247, v247
	v_fma_f32 v84, v84, v247, v247
	v_fma_f32 v85, v85, v247, v247
	v_fma_f32 v86, v86, v247, v247
	v_fma_f32 v87, v87, v247, v247
	v_rcp_f32_e32 v92, v92
	v_rcp_f32_e32 v93, v93
	v_rcp_f32_e32 v94, v94
	v_rcp_f32_e32 v95, v95
	v_rcp_f32_e32 v84, v84
	v_rcp_f32_e32 v85, v85
	v_rcp_f32_e32 v86, v86
	v_rcp_f32_e32 v87, v87
	v_mul_f32_e32 v88, v88, v92
	v_mul_f32_e32 v89, v89, v93
	v_mul_f32_e32 v90, v90, v94
	v_mul_f32_e32 v91, v91, v95
	v_mul_f32_e32 v80, v80, v84
	v_mul_f32_e32 v81, v81, v85
	v_mul_f32_e32 v82, v82, v86
	v_mul_f32_e32 v83, v83, v87
	v_cvt_pk_bf16_f32 v92, v88, v89
	v_cvt_pk_bf16_f32 v93, v90, v91
	v_cvt_pk_bf16_f32 v94, v80, v81
	v_cvt_pk_bf16_f32 v95, v82, v83
	v_add_u32_e32 v81, 0xb000, v97
	v_add_lshl_u32 v80, v81, v139, 1
	buffer_store_dwordx4 v[92:95], v80, s[36:39], 0 offen sc1
	s_nop 1
	v_mov_b32_e32 v80, v217
	s_waitcnt lgkmcnt(0)
	v_mul_f32_e32 v246, 0xbfb8aa3b, v80
	v_mul_f32_e32 v247, v80, v80
	v_rcp_f32_e32 v247, v247
	v_mul_f32_e32 v72, v72, v76
	v_mul_f32_e32 v73, v73, v77
	v_mul_f32_e32 v74, v74, v78
	v_mul_f32_e32 v75, v75, v79
	v_mul_f32_e32 v64, v64, v68
	v_mul_f32_e32 v65, v65, v69
	v_mul_f32_e32 v66, v66, v70
	v_mul_f32_e32 v67, v67, v71
	v_mul_f32_e32 v76, v246, v76
	v_mul_f32_e32 v77, v246, v77
	v_mul_f32_e32 v78, v246, v78
	v_mul_f32_e32 v79, v246, v79
	v_mul_f32_e32 v68, v246, v68
	v_mul_f32_e32 v69, v246, v69
	v_mul_f32_e32 v70, v246, v70
	v_mul_f32_e32 v71, v246, v71
	v_exp_f32_e32 v76, v76
	v_exp_f32_e32 v77, v77
	v_exp_f32_e32 v78, v78
	v_exp_f32_e32 v79, v79
	v_exp_f32_e32 v68, v68
	v_exp_f32_e32 v69, v69
	v_exp_f32_e32 v70, v70
	v_exp_f32_e32 v71, v71
	v_fma_f32 v76, v76, v247, v247
	v_fma_f32 v77, v77, v247, v247
	v_fma_f32 v78, v78, v247, v247
	v_fma_f32 v79, v79, v247, v247
	v_fma_f32 v68, v68, v247, v247
	v_fma_f32 v69, v69, v247, v247
	v_fma_f32 v70, v70, v247, v247
	v_fma_f32 v71, v71, v247, v247
	v_rcp_f32_e32 v76, v76
	v_rcp_f32_e32 v77, v77
	v_rcp_f32_e32 v78, v78
	v_rcp_f32_e32 v79, v79
	v_rcp_f32_e32 v68, v68
	v_rcp_f32_e32 v69, v69
	v_rcp_f32_e32 v70, v70
	v_rcp_f32_e32 v71, v71
	v_mul_f32_e32 v72, v72, v76
	v_mul_f32_e32 v73, v73, v77
	v_mul_f32_e32 v74, v74, v78
	v_mul_f32_e32 v75, v75, v79
	v_mul_f32_e32 v64, v64, v68
	v_mul_f32_e32 v65, v65, v69
	v_mul_f32_e32 v66, v66, v70
	v_mul_f32_e32 v67, v67, v71
	v_cvt_pk_bf16_f32 v76, v72, v73
	v_cvt_pk_bf16_f32 v77, v74, v75
	v_cvt_pk_bf16_f32 v78, v64, v65
	v_cvt_pk_bf16_f32 v79, v66, v67
	v_add_u32_e32 v65, 0xb000, v81
	v_add_lshl_u32 v64, v65, v139, 1
	buffer_store_dwordx4 v[76:79], v64, s[36:39], 0 offen sc1
	s_nop 1
	v_add_u32_e32 v66, 0x80, v138
	v_mov_b32_e32 v64, v218
	s_waitcnt lgkmcnt(0)
	v_mul_f32_e32 v246, 0xbfb8aa3b, v64
	v_mul_f32_e32 v247, v64, v64
	v_rcp_f32_e32 v247, v247
	v_mul_f32_e32 v56, v56, v60
	v_mul_f32_e32 v57, v57, v61
	v_mul_f32_e32 v58, v58, v62
	v_mul_f32_e32 v59, v59, v63
	v_mul_f32_e32 v48, v48, v52
	v_mul_f32_e32 v49, v49, v53
	v_mul_f32_e32 v50, v50, v54
	v_mul_f32_e32 v51, v51, v55
	v_mul_f32_e32 v60, v246, v60
	v_mul_f32_e32 v61, v246, v61
	v_mul_f32_e32 v62, v246, v62
	v_mul_f32_e32 v63, v246, v63
	v_mul_f32_e32 v52, v246, v52
	v_mul_f32_e32 v53, v246, v53
	v_mul_f32_e32 v54, v246, v54
	v_mul_f32_e32 v55, v246, v55
	v_exp_f32_e32 v60, v60
	v_exp_f32_e32 v61, v61
	v_exp_f32_e32 v62, v62
	v_exp_f32_e32 v63, v63
	v_exp_f32_e32 v52, v52
	v_exp_f32_e32 v53, v53
	v_exp_f32_e32 v54, v54
	v_exp_f32_e32 v55, v55
	v_fma_f32 v60, v60, v247, v247
	v_fma_f32 v61, v61, v247, v247
	v_fma_f32 v62, v62, v247, v247
	v_fma_f32 v63, v63, v247, v247
	v_fma_f32 v52, v52, v247, v247
	v_fma_f32 v53, v53, v247, v247
	v_fma_f32 v54, v54, v247, v247
	v_fma_f32 v55, v55, v247, v247
	v_rcp_f32_e32 v60, v60
	v_rcp_f32_e32 v61, v61
	v_rcp_f32_e32 v62, v62
	v_rcp_f32_e32 v63, v63
	v_rcp_f32_e32 v52, v52
	v_rcp_f32_e32 v53, v53
	v_rcp_f32_e32 v54, v54
	v_rcp_f32_e32 v55, v55
	v_mul_f32_e32 v56, v56, v60
	v_mul_f32_e32 v57, v57, v61
	v_mul_f32_e32 v58, v58, v62
	v_mul_f32_e32 v59, v59, v63
	v_mul_f32_e32 v48, v48, v52
	v_mul_f32_e32 v49, v49, v53
	v_mul_f32_e32 v50, v50, v54
	v_mul_f32_e32 v51, v51, v55
	v_cvt_pk_bf16_f32 v60, v56, v57
	v_cvt_pk_bf16_f32 v61, v58, v59
	v_cvt_pk_bf16_f32 v62, v48, v49
	v_cvt_pk_bf16_f32 v63, v50, v51
	v_add_u32_e32 v49, 0x37000, v65
	v_add_lshl_u32 v48, v49, v139, 1
	buffer_store_dwordx4 v[60:63], v48, s[36:39], 0 offen sc1
	s_nop 1
	v_add_u32_e32 v50, 0x90, v138
	v_mov_b32_e32 v48, v219
	s_waitcnt lgkmcnt(0)
	v_mul_f32_e32 v246, 0xbfb8aa3b, v48
	v_mul_f32_e32 v247, v48, v48
	v_rcp_f32_e32 v247, v247
	v_mul_f32_e32 v40, v40, v44
	v_mul_f32_e32 v41, v41, v45
	v_mul_f32_e32 v42, v42, v46
	v_mul_f32_e32 v43, v43, v47
	v_mul_f32_e32 v32, v32, v36
	v_mul_f32_e32 v33, v33, v37
	v_mul_f32_e32 v34, v34, v38
	v_mul_f32_e32 v35, v35, v39
	v_mul_f32_e32 v44, v246, v44
	v_mul_f32_e32 v45, v246, v45
	v_mul_f32_e32 v46, v246, v46
	v_mul_f32_e32 v47, v246, v47
	v_mul_f32_e32 v36, v246, v36
	v_mul_f32_e32 v37, v246, v37
	v_mul_f32_e32 v38, v246, v38
	v_mul_f32_e32 v39, v246, v39
	v_exp_f32_e32 v44, v44
	v_exp_f32_e32 v45, v45
	v_exp_f32_e32 v46, v46
	v_exp_f32_e32 v47, v47
	v_exp_f32_e32 v36, v36
	v_exp_f32_e32 v37, v37
	v_exp_f32_e32 v38, v38
	v_exp_f32_e32 v39, v39
	v_fma_f32 v44, v44, v247, v247
	v_fma_f32 v45, v45, v247, v247
	v_fma_f32 v46, v46, v247, v247
	v_fma_f32 v47, v47, v247, v247
	v_fma_f32 v36, v36, v247, v247
	v_fma_f32 v37, v37, v247, v247
	v_fma_f32 v38, v38, v247, v247
	v_fma_f32 v39, v39, v247, v247
	v_rcp_f32_e32 v44, v44
	v_rcp_f32_e32 v45, v45
	v_rcp_f32_e32 v46, v46
	v_rcp_f32_e32 v47, v47
	v_rcp_f32_e32 v36, v36
	v_rcp_f32_e32 v37, v37
	v_rcp_f32_e32 v38, v38
	v_rcp_f32_e32 v39, v39
	v_mul_f32_e32 v40, v40, v44
	v_mul_f32_e32 v41, v41, v45
	v_mul_f32_e32 v42, v42, v46
	v_mul_f32_e32 v43, v43, v47
	v_mul_f32_e32 v32, v32, v36
	v_mul_f32_e32 v33, v33, v37
	v_mul_f32_e32 v34, v34, v38
	v_mul_f32_e32 v35, v35, v39
	v_cvt_pk_bf16_f32 v44, v40, v41
	v_cvt_pk_bf16_f32 v45, v42, v43
	v_cvt_pk_bf16_f32 v46, v32, v33
	v_cvt_pk_bf16_f32 v47, v34, v35
	v_add_u32_e32 v35, 0xb000, v49
	v_add_lshl_u32 v32, v35, v139, 1
	buffer_store_dwordx4 v[44:47], v32, s[36:39], 0 offen sc1
	v_add_u32_e32 v32, 0xa0, v138
	v_mov_b32_e32 v34, v220
	s_waitcnt lgkmcnt(0)
	v_mul_f32_e32 v246, 0xbfb8aa3b, v34
	v_mul_f32_e32 v247, v34, v34
	v_rcp_f32_e32 v247, v247
	v_mul_f32_e32 v24, v24, v28
	v_mul_f32_e32 v25, v25, v29
	v_mul_f32_e32 v26, v26, v30
	v_mul_f32_e32 v27, v27, v31
	v_mul_f32_e32 v16, v16, v20
	v_mul_f32_e32 v17, v17, v21
	v_mul_f32_e32 v18, v18, v22
	v_mul_f32_e32 v19, v19, v23
	v_mul_f32_e32 v28, v246, v28
	v_mul_f32_e32 v29, v246, v29
	v_mul_f32_e32 v30, v246, v30
	v_mul_f32_e32 v31, v246, v31
	v_mul_f32_e32 v20, v246, v20
	v_mul_f32_e32 v21, v246, v21
	v_mul_f32_e32 v22, v246, v22
	v_mul_f32_e32 v23, v246, v23
	v_exp_f32_e32 v28, v28
	v_exp_f32_e32 v29, v29
	v_exp_f32_e32 v30, v30
	v_exp_f32_e32 v31, v31
	v_exp_f32_e32 v20, v20
	v_exp_f32_e32 v21, v21
	v_exp_f32_e32 v22, v22
	v_exp_f32_e32 v23, v23
	v_fma_f32 v28, v28, v247, v247
	v_fma_f32 v29, v29, v247, v247
	v_fma_f32 v30, v30, v247, v247
	v_fma_f32 v31, v31, v247, v247
	v_fma_f32 v20, v20, v247, v247
	v_fma_f32 v21, v21, v247, v247
	v_fma_f32 v22, v22, v247, v247
	v_fma_f32 v23, v23, v247, v247
	v_rcp_f32_e32 v28, v28
	v_rcp_f32_e32 v29, v29
	v_rcp_f32_e32 v30, v30
	v_rcp_f32_e32 v31, v31
	v_rcp_f32_e32 v20, v20
	v_rcp_f32_e32 v21, v21
	v_rcp_f32_e32 v22, v22
	v_rcp_f32_e32 v23, v23
	v_mul_f32_e32 v24, v24, v28
	v_mul_f32_e32 v25, v25, v29
	v_mul_f32_e32 v26, v26, v30
	v_mul_f32_e32 v27, v27, v31
	v_mul_f32_e32 v16, v16, v20
	v_mul_f32_e32 v17, v17, v21
	v_mul_f32_e32 v18, v18, v22
	v_mul_f32_e32 v19, v19, v23
	v_cvt_pk_bf16_f32 v28, v24, v25
	v_cvt_pk_bf16_f32 v29, v26, v27
	v_cvt_pk_bf16_f32 v30, v16, v17
	v_cvt_pk_bf16_f32 v31, v18, v19
	v_add_u32_e32 v17, 0xb000, v35
	v_add_lshl_u32 v16, v17, v139, 1
	buffer_store_dwordx4 v[28:31], v16, s[36:39], 0 offen sc1
	s_nop 1
	v_add_u32_e32 v18, 0xb0, v138
	v_mov_b32_e32 v16, v221
	s_branch .LBB0_788
